# residual-epilogue phases (Wout, FFN-down): their f32 stores made write-through (sc1) so the pre-barrier L2 write-back has less to flush
# speedup vs baseline: 1.0028x; 1.0025x over previous
.LBB0_1095:
	s_or_b64 exec, exec, s[18:19]
	v_lshl_add_u64 v[224:225], v[202:203], 0, v[190:191]
	global_load_dwordx4 v[200:203], v[224:225], off
	global_load_dwordx4 v[216:219], v[224:225], off offset:64
	global_load_dwordx4 v[220:223], v[224:225], off offset:512
	s_nop 0
	global_load_dwordx4 v[224:227], v[224:225], off offset:576
	v_lshlrev_b64 v[228:229], 12, v[192:193]
	v_lshl_add_u64 v[228:229], s[88:89], 0, v[228:229]
	v_lshl_add_u64 v[228:229], v[228:229], 0, v[190:191]
	s_waitcnt vmcnt(0)
	v_pk_add_f32 v[110:111], v[110:111], v[158:159]
	v_pk_add_f32 v[108:109], v[108:109], v[156:157]
	global_store_dwordx4 v[228:229], v[108:111], off offset:576 sc1
	v_pk_add_f32 v[118:119], v[118:119], v[166:167]
	v_pk_add_f32 v[116:117], v[116:117], v[164:165]
	v_lshlrev_b64 v[108:109], 12, v[198:199]
	v_lshl_add_u64 v[108:109], s[88:89], 0, v[108:109]
	global_store_dwordx4 v[228:229], v[116:119], off offset:512 sc1
	v_pk_add_f32 v[94:95], v[94:95], v[142:143]
	v_pk_add_f32 v[92:93], v[92:93], v[140:141]
	v_lshl_add_u64 v[116:117], v[108:109], 0, v[190:191]
	global_store_dwordx4 v[116:117], v[92:95], off offset:576 sc1
	v_pk_add_f32 v[102:103], v[102:103], v[150:151]
	v_pk_add_f32 v[100:101], v[100:101], v[148:149]
	v_lshlrev_b64 v[92:93], 12, v[194:195]
	v_lshl_add_u64 v[92:93], s[88:89], 0, v[92:93]
	global_store_dwordx4 v[116:117], v[100:103], off offset:512 sc1
	v_pk_add_f32 v[74:75], v[74:75], v[130:131]
	v_pk_add_f32 v[72:73], v[72:73], v[128:129]
	v_lshl_add_u64 v[100:101], v[92:93], 0, v[190:191]
	v_pk_add_f32 v[82:83], v[82:83], v[134:135]
	v_pk_add_f32 v[80:81], v[80:81], v[132:133]
	global_store_dwordx4 v[100:101], v[72:75], off offset:576 sc1
	v_pk_add_f32 v[126:127], v[126:127], v[174:175]
	v_pk_add_f32 v[124:125], v[124:125], v[172:173]
	v_lshl_add_u64 v[72:73], s[88:89], 0, v[196:197]
	v_pk_add_f32 v[122:123], v[122:123], v[170:171]
	v_pk_add_f32 v[120:121], v[120:121], v[168:169]
	v_pk_add_f32 v[110:111], v[114:115], v[162:163]
	v_pk_add_f32 v[108:109], v[112:113], v[160:161]
	v_pk_add_f32 v[106:107], v[106:107], v[154:155]
	v_pk_add_f32 v[104:105], v[104:105], v[152:153]
	v_pk_add_f32 v[94:95], v[98:99], v[146:147]
	v_pk_add_f32 v[92:93], v[96:97], v[144:145]
	v_pk_add_f32 v[90:91], v[90:91], v[138:139]
	v_pk_add_f32 v[88:89], v[88:89], v[136:137]
	global_store_dwordx4 v[100:101], v[80:83], off offset:512 sc1
	v_pk_add_f32 v[74:75], v[86:87], v[202:203]
	global_store_dwordx4 v[228:229], v[124:127], off sc1
	v_lshl_add_u64 v[80:81], v[72:73], 0, v[190:191]
	v_pk_add_f32 v[72:73], v[84:85], v[200:201]
	global_store_dwordx4 v[228:229], v[120:123], off offset:64 sc1
	global_store_dwordx4 v[116:117], v[108:111], off sc1
	global_store_dwordx4 v[116:117], v[104:107], off offset:64 sc1
	global_store_dwordx4 v[100:101], v[92:95], off sc1
	global_store_dwordx4 v[100:101], v[88:91], off offset:64 sc1
	global_store_dwordx4 v[80:81], v[72:75], off sc1
	v_pk_add_f32 v[70:71], v[70:71], v[222:223]
	v_pk_add_f32 v[68:69], v[68:69], v[220:221]
	v_pk_add_f32 v[74:75], v[78:79], v[218:219]
	v_pk_add_f32 v[72:73], v[76:77], v[216:217]
	v_pk_add_f32 v[66:67], v[66:67], v[226:227]
	v_pk_add_f32 v[64:65], v[64:65], v[224:225]
	global_store_dwordx4 v[80:81], v[72:75], off offset:64 sc1
	global_store_dwordx4 v[80:81], v[68:71], off offset:512 sc1
	global_store_dwordx4 v[80:81], v[64:67], off offset:576 sc1
	v_add_u32_e32 v118, 0x80, v192
	v_readlane_b32 s52, v254, 3
	v_ashrrev_i32_e32 v119, 31, v118
	v_add_u32_e32 v64, 0xffffc080, v192
	v_cmp_gt_i32_e32 vcc, s46, v192
	v_readlane_b32 s53, v254, 4
	v_readlane_b32 s54, v254, 5
	v_readlane_b32 s55, v254, 6
	v_cndmask_b32_e32 v65, 0, v119, vcc
	v_cndmask_b32_e32 v64, v64, v118, vcc
	v_mov_b32_e32 v68, s55
	v_mov_b32_e32 v69, s53
	v_mov_b32_e32 v70, s54
	v_mov_b32_e32 v71, s52
	v_cndmask_b32_e32 v67, v68, v69, vcc
	v_cndmask_b32_e32 v66, v70, v71, vcc
	v_lshlrev_b64 v[64:65], 12, v[64:65]
	v_lshl_add_u64 v[64:65], v[66:67], 0, v[64:65]
	v_lshl_add_u64 v[64:65], v[64:65], 0, v[190:191]
	v_add_u32_e32 v116, 0x90, v192
	global_load_dwordx4 v[108:111], v[64:65], off
	global_load_dwordx4 v[104:107], v[64:65], off offset:64
	global_load_dwordx4 v[100:103], v[64:65], off offset:512
	global_load_dwordx4 v[92:95], v[64:65], off offset:576
	v_ashrrev_i32_e32 v117, 31, v116
	v_add_u32_e32 v64, 0xffffc090, v192
	v_cmp_gt_i32_e32 vcc, s47, v192
	v_add_u32_e32 v112, 0xa0, v192
	v_ashrrev_i32_e32 v113, 31, v112
	v_cndmask_b32_e32 v65, 0, v117, vcc
	v_cndmask_b32_e32 v64, v64, v116, vcc
	v_cndmask_b32_e32 v67, v68, v69, vcc
	v_cndmask_b32_e32 v66, v70, v71, vcc
	v_lshlrev_b64 v[64:65], 12, v[64:65]
	v_lshl_add_u64 v[64:65], v[66:67], 0, v[64:65]
	v_lshl_add_u64 v[64:65], v[64:65], 0, v[190:191]
	global_load_dwordx4 v[96:99], v[64:65], off
	global_load_dwordx4 v[88:91], v[64:65], off offset:64
	global_load_dwordx4 v[84:87], v[64:65], off offset:512
	global_load_dwordx4 v[76:79], v[64:65], off offset:576
	v_add_u32_e32 v64, 0xffffc0a0, v192
	v_cmp_gt_i32_e32 vcc, s48, v192
	v_add_u32_e32 v120, 0xb0, v192
	v_readlane_b32 s56, v254, 7
	v_cndmask_b32_e32 v65, 0, v113, vcc
	v_cndmask_b32_e32 v64, v64, v112, vcc
	v_cndmask_b32_e32 v67, v68, v69, vcc
	v_cndmask_b32_e32 v66, v70, v71, vcc
	v_lshlrev_b64 v[64:65], 12, v[64:65]
	v_lshl_add_u64 v[64:65], v[66:67], 0, v[64:65]
	v_lshl_add_u64 v[64:65], v[64:65], 0, v[190:191]
	global_load_dwordx4 v[80:83], v[64:65], off
	global_load_dwordx4 v[72:75], v[64:65], off offset:64
	global_load_dwordx4 v[68:71], v[64:65], off offset:512
	s_nop 0
	global_load_dwordx4 v[64:67], v[64:65], off offset:576
	v_cmp_lt_i32_e32 vcc, s49, v192
	v_readlane_b32 s57, v254, 8
	v_readlane_b32 s58, v254, 9
	v_readlane_b32 s59, v254, 10
	v_readlane_b32 s60, v254, 11
	v_readlane_b32 s61, v254, 12
	v_readlane_b32 s62, v254, 13
	v_readlane_b32 s63, v254, 14
	v_readlane_b32 s64, v254, 15
	v_readlane_b32 s65, v254, 16
	v_readlane_b32 s66, v254, 17
	v_readlane_b32 s67, v254, 18
	s_and_saveexec_b64 s[18:19], vcc
	s_xor_b64 s[18:19], exec, s[18:19]
	s_cbranch_execz .LBB0_1097
	v_add_u32_e32 v180, 0xffffc0b0, v192
	v_readlane_b32 s52, v254, 3
	v_lshlrev_b64 v[114:115], 12, v[180:181]
	v_readlane_b32 s54, v254, 5
	v_readlane_b32 s55, v254, 6
	v_mov_b32_e32 v121, v181
	v_readlane_b32 s53, v254, 4
	v_lshl_add_u64 v[122:123], s[54:55], 0, v[114:115]
	v_lshlrev_b64 v[114:115], 12, v[120:121]
	v_readlane_b32 s56, v254, 7
	v_readlane_b32 s57, v254, 8
	v_readlane_b32 s58, v254, 9
	v_readlane_b32 s59, v254, 10
	v_readlane_b32 s60, v254, 11
	v_readlane_b32 s61, v254, 12
	v_readlane_b32 s62, v254, 13
	v_readlane_b32 s63, v254, 14
	v_readlane_b32 s64, v254, 15
	v_readlane_b32 s65, v254, 16
	v_readlane_b32 s66, v254, 17
	v_readlane_b32 s67, v254, 18

.LBB0_1099:
	s_or_b64 exec, exec, s[18:19]
	v_lshl_add_u64 v[132:133], v[122:123], 0, v[190:191]
	global_load_dwordx4 v[120:123], v[132:133], off
	global_load_dwordx4 v[124:127], v[132:133], off offset:64
	global_load_dwordx4 v[128:131], v[132:133], off offset:512
	s_nop 0
	global_load_dwordx4 v[132:135], v[132:133], off offset:576
	v_lshlrev_b64 v[118:119], 12, v[118:119]
	v_lshl_add_u64 v[118:119], s[88:89], 0, v[118:119]
	v_lshl_add_u64 v[118:119], v[118:119], 0, v[190:191]
	s_waitcnt vmcnt(12)
	v_pk_add_f32 v[46:47], v[46:47], v[94:95]
	v_pk_add_f32 v[44:45], v[44:45], v[92:93]
	global_store_dwordx4 v[118:119], v[44:47], off offset:576 sc1
	v_pk_add_f32 v[54:55], v[54:55], v[102:103]
	v_pk_add_f32 v[52:53], v[52:53], v[100:101]
	v_lshlrev_b64 v[44:45], 12, v[116:117]
	v_lshl_add_u64 v[44:45], s[88:89], 0, v[44:45]
	global_store_dwordx4 v[118:119], v[52:55], off offset:512 sc1
	s_waitcnt vmcnt(10)
	v_pk_add_f32 v[30:31], v[30:31], v[78:79]
	v_pk_add_f32 v[28:29], v[28:29], v[76:77]
	v_lshl_add_u64 v[52:53], v[44:45], 0, v[190:191]
	global_store_dwordx4 v[52:53], v[28:31], off offset:576 sc1
	v_pk_add_f32 v[38:39], v[38:39], v[86:87]
	v_pk_add_f32 v[36:37], v[36:37], v[84:85]
	v_lshlrev_b64 v[28:29], 12, v[112:113]
	v_lshl_add_u64 v[28:29], s[88:89], 0, v[28:29]
	global_store_dwordx4 v[52:53], v[36:39], off offset:512 sc1
	s_waitcnt vmcnt(8)
	v_pk_add_f32 v[10:11], v[10:11], v[66:67]
	v_pk_add_f32 v[8:9], v[8:9], v[64:65]
	v_lshl_add_u64 v[36:37], v[28:29], 0, v[190:191]
	v_pk_add_f32 v[18:19], v[18:19], v[70:71]
	v_pk_add_f32 v[16:17], v[16:17], v[68:69]
	global_store_dwordx4 v[36:37], v[8:11], off offset:576 sc1
	v_pk_add_f32 v[62:63], v[62:63], v[110:111]
	v_pk_add_f32 v[60:61], v[60:61], v[108:109]
	v_lshl_add_u64 v[8:9], s[88:89], 0, v[114:115]
	v_pk_add_f32 v[58:59], v[58:59], v[106:107]
	v_pk_add_f32 v[56:57], v[56:57], v[104:105]
	v_pk_add_f32 v[46:47], v[50:51], v[98:99]
	v_pk_add_f32 v[44:45], v[48:49], v[96:97]
	v_pk_add_f32 v[42:43], v[42:43], v[90:91]
	v_pk_add_f32 v[40:41], v[40:41], v[88:89]
	v_pk_add_f32 v[30:31], v[34:35], v[82:83]
	v_pk_add_f32 v[28:29], v[32:33], v[80:81]
	v_pk_add_f32 v[26:27], v[26:27], v[74:75]
	v_pk_add_f32 v[24:25], v[24:25], v[72:73]
	global_store_dwordx4 v[36:37], v[16:19], off offset:512 sc1
	s_waitcnt vmcnt(9)
	v_pk_add_f32 v[10:11], v[22:23], v[122:123]
	global_store_dwordx4 v[118:119], v[60:63], off sc1
	v_lshl_add_u64 v[16:17], v[8:9], 0, v[190:191]
	v_pk_add_f32 v[8:9], v[20:21], v[120:121]
	global_store_dwordx4 v[118:119], v[56:59], off offset:64 sc1
	global_store_dwordx4 v[52:53], v[44:47], off sc1
	global_store_dwordx4 v[52:53], v[40:43], off offset:64 sc1
	global_store_dwordx4 v[36:37], v[28:31], off sc1
	global_store_dwordx4 v[36:37], v[24:27], off offset:64 sc1
	global_store_dwordx4 v[16:17], v[8:11], off sc1
	s_waitcnt vmcnt(14)
	v_pk_add_f32 v[6:7], v[6:7], v[130:131]
	v_pk_add_f32 v[4:5], v[4:5], v[128:129]
	v_pk_add_f32 v[10:11], v[14:15], v[126:127]
	v_pk_add_f32 v[8:9], v[12:13], v[124:125]
	s_waitcnt vmcnt(13)
	v_pk_add_f32 v[2:3], v[2:3], v[134:135]
	v_pk_add_f32 v[0:1], v[0:1], v[132:133]
	global_store_dwordx4 v[16:17], v[8:11], off offset:64 sc1
	global_store_dwordx4 v[16:17], v[4:7], off offset:512 sc1
	global_store_dwordx4 v[16:17], v[0:3], off offset:576 sc1
	s_andn2_b64 vcc, exec, s[2:3]
	s_mov_b64 s[2:3], -1
	s_cbranch_vccnz .LBB0_1080
	s_andn2_b64 vcc, exec, s[0:1]
	s_cbranch_vccnz .LBB0_1079
	v_writelane_b32 v255, 1, 53
	s_branch .LBB0_1079

.LBB0_1113:
	s_ashr_i32 s17, s46, 31
	s_lshr_b32 s17, s17, 24
	s_add_i32 s17, s46, s17
	s_ashr_i32 s26, s17, 8
	v_lshl_add_u32 v136, s45, 8, v128
	s_ashr_i32 s27, s26, 31
	v_ashrrev_i32_e32 v137, 31, v136
	v_lshl_or_b32 v138, s44, 8, v129
	s_lshl_b64 s[26:27], s[26:27], 21
	v_lshlrev_b64 v[136:137], 12, v[136:137]
	v_ashrrev_i32_e32 v139, 31, v138
	v_lshl_add_u64 v[136:137], v[136:137], 0, s[26:27]
	v_lshl_add_u64 v[140:141], s[6:7], 0, v[136:137]
	v_lshlrev_b64 v[138:139], 2, v[138:139]
	v_lshl_add_u64 v[140:141], v[140:141], 0, v[138:139]
	global_store_dwordx4 v[140:141], v[24:27], off sc1
	global_store_dwordx4 v[140:141], v[28:31], off offset:64 sc1
	global_store_dwordx4 v[140:141], v[56:59], off offset:512 sc1
	global_store_dwordx4 v[140:141], v[60:63], off offset:576 sc1
	v_or_b32_e32 v24, 0x10000, v136
	v_mov_b32_e32 v25, v137
	v_lshl_add_u64 v[24:25], s[6:7], 0, v[24:25]
	v_lshl_add_u64 v[24:25], v[24:25], 0, v[138:139]
	global_store_dwordx4 v[24:25], v[16:19], off sc1
	global_store_dwordx4 v[24:25], v[20:23], off offset:64 sc1
	global_store_dwordx4 v[24:25], v[48:51], off offset:512 sc1
	global_store_dwordx4 v[24:25], v[52:55], off offset:576 sc1
	v_or_b32_e32 v16, 0x20000, v136
	v_mov_b32_e32 v17, v137
	v_lshl_add_u64 v[16:17], s[6:7], 0, v[16:17]
	v_lshl_add_u64 v[16:17], v[16:17], 0, v[138:139]
	v_or_b32_e32 v136, 0x30000, v136
	global_store_dwordx4 v[16:17], v[8:11], off sc1
	global_store_dwordx4 v[16:17], v[12:15], off offset:64 sc1
	global_store_dwordx4 v[16:17], v[40:43], off offset:512 sc1
	global_store_dwordx4 v[16:17], v[44:47], off offset:576 sc1
	v_lshl_add_u64 v[8:9], s[6:7], 0, v[136:137]
	v_lshl_add_u64 v[8:9], v[8:9], 0, v[138:139]
	global_store_dwordx4 v[8:9], v[0:3], off sc1
	global_store_dwordx4 v[8:9], v[4:7], off offset:64 sc1
	global_store_dwordx4 v[8:9], v[32:35], off offset:512 sc1
	global_store_dwordx4 v[8:9], v[36:39], off offset:576 sc1
	v_add_co_u32_e32 v2, vcc, s56, v140
	s_mov_b64 s[26:27], 0x80000
	s_nop 0
	v_addc_co_u32_e32 v3, vcc, 0, v141, vcc
	v_lshl_add_u64 v[0:1], v[140:141], 0, s[26:27]
	global_store_dwordx4 v[2:3], v[92:95], off sc1
	global_store_dwordx4 v[0:1], v[100:103], off offset:64 sc1
	global_store_dwordx4 v[0:1], v[120:123], off offset:512 sc1
	global_store_dwordx4 v[0:1], v[124:127], off offset:576 sc1
	v_add_co_u32_e32 v2, vcc, s57, v140
	v_lshl_add_u64 v[0:1], v[140:141], 0, s[10:11]
	s_nop 0
	v_addc_co_u32_e32 v3, vcc, 0, v141, vcc
	global_store_dwordx4 v[2:3], v[80:83], off sc1
	global_store_dwordx4 v[0:1], v[84:87], off offset:64 sc1
	global_store_dwordx4 v[0:1], v[112:115], off offset:512 sc1
	global_store_dwordx4 v[0:1], v[116:119], off offset:576 sc1
	v_add_co_u32_e32 v2, vcc, s58, v140
	v_lshl_add_u64 v[0:1], v[140:141], 0, s[12:13]
	s_nop 0
	v_addc_co_u32_e32 v3, vcc, 0, v141, vcc
	global_store_dwordx4 v[2:3], v[72:75], off sc1
	global_store_dwordx4 v[0:1], v[76:79], off offset:64 sc1
	global_store_dwordx4 v[0:1], v[104:107], off offset:512 sc1
	global_store_dwordx4 v[0:1], v[108:111], off offset:576 sc1
	v_add_co_u32_e32 v2, vcc, 0xb0000, v140
	v_lshl_add_u64 v[0:1], v[140:141], 0, s[14:15]
	s_nop 0
	v_addc_co_u32_e32 v3, vcc, 0, v141, vcc
	s_andn2_b64 vcc, exec, s[22:23]
	s_mov_b64 s[22:23], -1
	global_store_dwordx4 v[2:3], v[64:67], off sc1
	global_store_dwordx4 v[0:1], v[68:71], off offset:64 sc1
	global_store_dwordx4 v[0:1], v[88:91], off offset:512 sc1
	global_store_dwordx4 v[0:1], v[96:99], off offset:576 sc1
	s_cbranch_vccnz .LBB0_1108
	s_andn2_b64 vcc, exec, s[0:1]
	s_cbranch_vccnz .LBB0_1107
	s_barrier
	s_branch .LBB0_1107

.LBB0_1327:
	v_lshl_add_u32 v192, s48, 8, v209
	v_add_u32_e32 v130, 0xffffc000, v192
	v_ashrrev_i32_e32 v193, 31, v192
	v_cmp_gt_i32_e32 vcc, s28, v192
	v_lshl_or_b32 v128, s49, 8, v211
	v_mov_b32_e32 v134, s9
	v_cndmask_b32_e32 v131, 0, v193, vcc
	v_cndmask_b32_e32 v130, v130, v192, vcc
	v_mov_b32_e32 v135, s89
	v_mov_b32_e32 v136, s8
	v_mov_b32_e32 v137, s88
	v_ashrrev_i32_e32 v129, 31, v128
	v_cndmask_b32_e32 v133, v134, v135, vcc
	v_cndmask_b32_e32 v132, v136, v137, vcc
	v_lshlrev_b64 v[130:131], 12, v[130:131]
	v_lshl_add_u64 v[130:131], v[132:133], 0, v[130:131]
	v_lshlrev_b64 v[190:191], 2, v[128:129]
	v_lshl_add_u64 v[128:129], v[130:131], 0, v[190:191]
	v_or_b32_e32 v198, 16, v192
	global_load_dwordx4 v[172:175], v[128:129], off
	global_load_dwordx4 v[168:171], v[128:129], off offset:64
	global_load_dwordx4 v[164:167], v[128:129], off offset:512
	global_load_dwordx4 v[156:159], v[128:129], off offset:576
	v_ashrrev_i32_e32 v199, 31, v198
	v_add_u32_e32 v128, 0xffffc010, v192
	v_cmp_gt_i32_e32 vcc, s28, v198
	v_or_b32_e32 v196, 32, v192
	v_ashrrev_i32_e32 v197, 31, v196
	v_cndmask_b32_e32 v129, 0, v199, vcc
	v_cndmask_b32_e32 v128, v128, v198, vcc
	v_cndmask_b32_e32 v131, v134, v135, vcc
	v_cndmask_b32_e32 v130, v136, v137, vcc
	v_lshlrev_b64 v[128:129], 12, v[128:129]
	v_lshl_add_u64 v[128:129], v[130:131], 0, v[128:129]
	v_lshl_add_u64 v[128:129], v[128:129], 0, v[190:191]
	global_load_dwordx4 v[160:163], v[128:129], off
	global_load_dwordx4 v[152:155], v[128:129], off offset:64
	global_load_dwordx4 v[148:151], v[128:129], off offset:512
	global_load_dwordx4 v[140:143], v[128:129], off offset:576
	v_add_u32_e32 v128, 0xffffc020, v192
	v_cmp_gt_i32_e32 vcc, s28, v196
	v_or_b32_e32 v200, 48, v192
	s_nop 0
	v_cndmask_b32_e32 v129, 0, v197, vcc
	v_cndmask_b32_e32 v128, v128, v196, vcc
	v_cndmask_b32_e32 v131, v134, v135, vcc
	v_cndmask_b32_e32 v130, v136, v137, vcc
	v_lshlrev_b64 v[128:129], 12, v[128:129]
	v_lshl_add_u64 v[128:129], v[130:131], 0, v[128:129]
	v_lshl_add_u64 v[128:129], v[128:129], 0, v[190:191]
	global_load_dwordx4 v[144:147], v[128:129], off
	global_load_dwordx4 v[136:139], v[128:129], off offset:64
	global_load_dwordx4 v[132:135], v[128:129], off offset:512
	s_nop 0
	global_load_dwordx4 v[128:131], v[128:129], off offset:576
	v_cmp_lt_i32_e32 vcc, s41, v200
	s_and_saveexec_b64 s[16:17], vcc
	s_xor_b64 s[16:17], exec, s[16:17]
	v_add_u32_e32 v180, 0xffffc030, v192
	v_lshlrev_b64 v[194:195], 12, v[180:181]
	v_mov_b32_e32 v201, v181
	v_lshl_add_u64 v[202:203], s[8:9], 0, v[194:195]
	v_lshlrev_b64 v[194:195], 12, v[200:201]
	s_andn2_saveexec_b64 s[16:17], s[16:17]
	v_ashrrev_i32_e32 v201, 31, v200
	v_lshlrev_b64 v[194:195], 12, v[200:201]
	v_lshl_add_u64 v[202:203], s[88:89], 0, v[194:195]
	s_or_b64 exec, exec, s[16:17]
	v_lshl_add_u64 v[224:225], v[202:203], 0, v[190:191]
	global_load_dwordx4 v[200:203], v[224:225], off
	global_load_dwordx4 v[216:219], v[224:225], off offset:64
	global_load_dwordx4 v[220:223], v[224:225], off offset:512
	s_nop 0
	global_load_dwordx4 v[224:227], v[224:225], off offset:576
	v_lshlrev_b64 v[228:229], 12, v[192:193]
	v_lshl_add_u64 v[228:229], s[88:89], 0, v[228:229]
	v_lshl_add_u64 v[228:229], v[228:229], 0, v[190:191]
	s_waitcnt vmcnt(0)
	v_pk_add_f32 v[110:111], v[110:111], v[158:159]
	v_pk_add_f32 v[108:109], v[108:109], v[156:157]
	global_store_dwordx4 v[228:229], v[108:111], off offset:576 sc1
	v_pk_add_f32 v[118:119], v[118:119], v[166:167]
	v_pk_add_f32 v[116:117], v[116:117], v[164:165]
	v_lshlrev_b64 v[108:109], 12, v[198:199]
	v_lshl_add_u64 v[108:109], s[88:89], 0, v[108:109]
	global_store_dwordx4 v[228:229], v[116:119], off offset:512 sc1
	v_pk_add_f32 v[94:95], v[94:95], v[142:143]
	v_pk_add_f32 v[92:93], v[92:93], v[140:141]
	v_lshl_add_u64 v[116:117], v[108:109], 0, v[190:191]
	global_store_dwordx4 v[116:117], v[92:95], off offset:576 sc1
	v_pk_add_f32 v[102:103], v[102:103], v[150:151]
	v_pk_add_f32 v[100:101], v[100:101], v[148:149]
	v_lshlrev_b64 v[92:93], 12, v[196:197]
	v_lshl_add_u64 v[92:93], s[88:89], 0, v[92:93]
	global_store_dwordx4 v[116:117], v[100:103], off offset:512 sc1
	v_pk_add_f32 v[74:75], v[74:75], v[130:131]
	v_pk_add_f32 v[72:73], v[72:73], v[128:129]
	v_lshl_add_u64 v[100:101], v[92:93], 0, v[190:191]
	v_pk_add_f32 v[82:83], v[82:83], v[134:135]
	v_pk_add_f32 v[80:81], v[80:81], v[132:133]
	global_store_dwordx4 v[100:101], v[72:75], off offset:576 sc1
	v_pk_add_f32 v[126:127], v[126:127], v[174:175]
	v_pk_add_f32 v[124:125], v[124:125], v[172:173]
	v_lshl_add_u64 v[72:73], s[88:89], 0, v[194:195]
	v_pk_add_f32 v[122:123], v[122:123], v[170:171]
	v_pk_add_f32 v[120:121], v[120:121], v[168:169]
	v_pk_add_f32 v[110:111], v[114:115], v[162:163]
	v_pk_add_f32 v[108:109], v[112:113], v[160:161]
	v_pk_add_f32 v[106:107], v[106:107], v[154:155]
	v_pk_add_f32 v[104:105], v[104:105], v[152:153]
	v_pk_add_f32 v[94:95], v[98:99], v[146:147]
	v_pk_add_f32 v[92:93], v[96:97], v[144:145]
	v_pk_add_f32 v[90:91], v[90:91], v[138:139]
	v_pk_add_f32 v[88:89], v[88:89], v[136:137]
	global_store_dwordx4 v[100:101], v[80:83], off offset:512 sc1
	v_pk_add_f32 v[74:75], v[86:87], v[202:203]
	global_store_dwordx4 v[228:229], v[124:127], off sc1
	v_lshl_add_u64 v[80:81], v[72:73], 0, v[190:191]
	v_pk_add_f32 v[72:73], v[84:85], v[200:201]
	global_store_dwordx4 v[228:229], v[120:123], off offset:64 sc1
	global_store_dwordx4 v[116:117], v[108:111], off sc1
	global_store_dwordx4 v[116:117], v[104:107], off offset:64 sc1
	global_store_dwordx4 v[100:101], v[92:95], off sc1
	global_store_dwordx4 v[100:101], v[88:91], off offset:64 sc1
	global_store_dwordx4 v[80:81], v[72:75], off sc1
	v_pk_add_f32 v[70:71], v[70:71], v[222:223]
	v_pk_add_f32 v[68:69], v[68:69], v[220:221]
	v_pk_add_f32 v[74:75], v[78:79], v[218:219]
	v_pk_add_f32 v[72:73], v[76:77], v[216:217]
	v_pk_add_f32 v[66:67], v[66:67], v[226:227]
	v_pk_add_f32 v[64:65], v[64:65], v[224:225]
	global_store_dwordx4 v[80:81], v[72:75], off offset:64 sc1
	global_store_dwordx4 v[80:81], v[68:71], off offset:512 sc1
	global_store_dwordx4 v[80:81], v[64:67], off offset:576 sc1
	v_add_u32_e32 v118, 0x80, v192
	v_ashrrev_i32_e32 v119, 31, v118
	v_add_u32_e32 v64, 0xffffc080, v192
	v_cmp_gt_i32_e32 vcc, s42, v192
	v_mov_b32_e32 v68, s9
	v_mov_b32_e32 v69, s89
	v_cndmask_b32_e32 v65, 0, v119, vcc
	v_cndmask_b32_e32 v64, v64, v118, vcc
	v_mov_b32_e32 v70, s8
	v_mov_b32_e32 v71, s88
	v_cndmask_b32_e32 v67, v68, v69, vcc
	v_cndmask_b32_e32 v66, v70, v71, vcc
	v_lshlrev_b64 v[64:65], 12, v[64:65]
	v_lshl_add_u64 v[64:65], v[66:67], 0, v[64:65]
	v_lshl_add_u64 v[64:65], v[64:65], 0, v[190:191]
	v_add_u32_e32 v116, 0x90, v192
	global_load_dwordx4 v[108:111], v[64:65], off
	global_load_dwordx4 v[104:107], v[64:65], off offset:64
	global_load_dwordx4 v[100:103], v[64:65], off offset:512
	global_load_dwordx4 v[92:95], v[64:65], off offset:576
	v_ashrrev_i32_e32 v117, 31, v116
	v_add_u32_e32 v64, 0xffffc090, v192
	v_cmp_gt_i32_e32 vcc, s43, v192
	v_add_u32_e32 v114, 0xa0, v192
	v_ashrrev_i32_e32 v115, 31, v114
	v_cndmask_b32_e32 v65, 0, v117, vcc
	v_cndmask_b32_e32 v64, v64, v116, vcc
	v_cndmask_b32_e32 v67, v68, v69, vcc
	v_cndmask_b32_e32 v66, v70, v71, vcc
	v_lshlrev_b64 v[64:65], 12, v[64:65]
	v_lshl_add_u64 v[64:65], v[66:67], 0, v[64:65]
	v_lshl_add_u64 v[64:65], v[64:65], 0, v[190:191]
	global_load_dwordx4 v[96:99], v[64:65], off
	global_load_dwordx4 v[88:91], v[64:65], off offset:64
	global_load_dwordx4 v[84:87], v[64:65], off offset:512
	global_load_dwordx4 v[76:79], v[64:65], off offset:576
	v_add_u32_e32 v64, 0xffffc0a0, v192
	v_cmp_gt_i32_e32 vcc, s44, v192
	v_add_u32_e32 v120, 0xb0, v192
	s_nop 0
	v_cndmask_b32_e32 v65, 0, v115, vcc
	v_cndmask_b32_e32 v64, v64, v114, vcc
	v_cndmask_b32_e32 v67, v68, v69, vcc
	v_cndmask_b32_e32 v66, v70, v71, vcc
	v_lshlrev_b64 v[64:65], 12, v[64:65]
	v_lshl_add_u64 v[64:65], v[66:67], 0, v[64:65]
	v_lshl_add_u64 v[64:65], v[64:65], 0, v[190:191]
	global_load_dwordx4 v[80:83], v[64:65], off
	global_load_dwordx4 v[72:75], v[64:65], off offset:64
	global_load_dwordx4 v[68:71], v[64:65], off offset:512
	s_nop 0
	global_load_dwordx4 v[64:67], v[64:65], off offset:576
	v_cmp_lt_i32_e32 vcc, s45, v192
	s_and_saveexec_b64 s[16:17], vcc
	s_xor_b64 s[16:17], exec, s[16:17]
	v_add_u32_e32 v180, 0xffffc0b0, v192
	v_lshlrev_b64 v[112:113], 12, v[180:181]
	v_mov_b32_e32 v121, v181
	v_lshl_add_u64 v[122:123], s[8:9], 0, v[112:113]
	v_lshlrev_b64 v[112:113], 12, v[120:121]
	s_andn2_saveexec_b64 s[16:17], s[16:17]
	v_ashrrev_i32_e32 v121, 31, v120
	v_lshlrev_b64 v[112:113], 12, v[120:121]
	v_lshl_add_u64 v[122:123], s[88:89], 0, v[112:113]
	s_or_b64 exec, exec, s[16:17]
	v_lshl_add_u64 v[132:133], v[122:123], 0, v[190:191]
	global_load_dwordx4 v[120:123], v[132:133], off
	global_load_dwordx4 v[124:127], v[132:133], off offset:64
	global_load_dwordx4 v[128:131], v[132:133], off offset:512
	s_nop 0
	global_load_dwordx4 v[132:135], v[132:133], off offset:576
	v_lshlrev_b64 v[118:119], 12, v[118:119]
	v_lshl_add_u64 v[118:119], s[88:89], 0, v[118:119]
	v_lshl_add_u64 v[118:119], v[118:119], 0, v[190:191]
	s_waitcnt vmcnt(12)
	v_pk_add_f32 v[46:47], v[46:47], v[94:95]
	v_pk_add_f32 v[44:45], v[44:45], v[92:93]
	global_store_dwordx4 v[118:119], v[44:47], off offset:576 sc1
	v_pk_add_f32 v[54:55], v[54:55], v[102:103]
	v_pk_add_f32 v[52:53], v[52:53], v[100:101]
	v_lshlrev_b64 v[44:45], 12, v[116:117]
	v_lshl_add_u64 v[44:45], s[88:89], 0, v[44:45]
	global_store_dwordx4 v[118:119], v[52:55], off offset:512 sc1
	s_waitcnt vmcnt(10)
	v_pk_add_f32 v[30:31], v[30:31], v[78:79]
	v_pk_add_f32 v[28:29], v[28:29], v[76:77]
	v_lshl_add_u64 v[52:53], v[44:45], 0, v[190:191]
	global_store_dwordx4 v[52:53], v[28:31], off offset:576 sc1
	v_pk_add_f32 v[38:39], v[38:39], v[86:87]
	v_pk_add_f32 v[36:37], v[36:37], v[84:85]
	v_lshlrev_b64 v[28:29], 12, v[114:115]
	v_lshl_add_u64 v[28:29], s[88:89], 0, v[28:29]
	global_store_dwordx4 v[52:53], v[36:39], off offset:512 sc1
	s_waitcnt vmcnt(8)
	v_pk_add_f32 v[10:11], v[10:11], v[66:67]
	v_pk_add_f32 v[8:9], v[8:9], v[64:65]
	v_lshl_add_u64 v[36:37], v[28:29], 0, v[190:191]
	v_pk_add_f32 v[18:19], v[18:19], v[70:71]
	v_pk_add_f32 v[16:17], v[16:17], v[68:69]
	global_store_dwordx4 v[36:37], v[8:11], off offset:576 sc1
	v_pk_add_f32 v[62:63], v[62:63], v[110:111]
	v_pk_add_f32 v[60:61], v[60:61], v[108:109]
	v_lshl_add_u64 v[8:9], s[88:89], 0, v[112:113]
	v_pk_add_f32 v[58:59], v[58:59], v[106:107]
	v_pk_add_f32 v[56:57], v[56:57], v[104:105]
	v_pk_add_f32 v[46:47], v[50:51], v[98:99]
	v_pk_add_f32 v[44:45], v[48:49], v[96:97]
	v_pk_add_f32 v[42:43], v[42:43], v[90:91]
	v_pk_add_f32 v[40:41], v[40:41], v[88:89]
	v_pk_add_f32 v[30:31], v[34:35], v[82:83]
	v_pk_add_f32 v[28:29], v[32:33], v[80:81]
	v_pk_add_f32 v[26:27], v[26:27], v[74:75]
	v_pk_add_f32 v[24:25], v[24:25], v[72:73]
	global_store_dwordx4 v[36:37], v[16:19], off offset:512 sc1
	s_waitcnt vmcnt(9)
	v_pk_add_f32 v[10:11], v[22:23], v[122:123]
	global_store_dwordx4 v[118:119], v[60:63], off sc1
	v_lshl_add_u64 v[16:17], v[8:9], 0, v[190:191]
	v_pk_add_f32 v[8:9], v[20:21], v[120:121]
	global_store_dwordx4 v[118:119], v[56:59], off offset:64 sc1
	global_store_dwordx4 v[52:53], v[44:47], off sc1
	global_store_dwordx4 v[52:53], v[40:43], off offset:64 sc1
	global_store_dwordx4 v[36:37], v[28:31], off sc1
	global_store_dwordx4 v[36:37], v[24:27], off offset:64 sc1
	global_store_dwordx4 v[16:17], v[8:11], off sc1
	s_waitcnt vmcnt(14)
	v_pk_add_f32 v[6:7], v[6:7], v[130:131]
	v_pk_add_f32 v[4:5], v[4:5], v[128:129]
	v_pk_add_f32 v[10:11], v[14:15], v[126:127]
	v_pk_add_f32 v[8:9], v[12:13], v[124:125]
	s_waitcnt vmcnt(13)
	v_pk_add_f32 v[2:3], v[2:3], v[134:135]
	v_pk_add_f32 v[0:1], v[0:1], v[132:133]
	global_store_dwordx4 v[16:17], v[8:11], off offset:64 sc1
	global_store_dwordx4 v[16:17], v[4:7], off offset:512 sc1
	global_store_dwordx4 v[16:17], v[0:3], off offset:576 sc1
	s_and_b64 vcc, exec, s[2:3]
	s_mov_b64 s[2:3], -1
	s_cbranch_vccnz .LBB0_1312
	s_andn2_b64 vcc, exec, s[6:7]
	s_cbranch_vccnz .LBB0_1311
	v_writelane_b32 v255, 1, 53
	s_branch .LBB0_1311

.LBB0_1355:
	s_ashr_i32 s12, s51, 31
	s_lshr_b32 s12, s12, 23
	s_add_i32 s12, s51, s12
	s_ashr_i32 s12, s12, 9
	v_lshl_add_u32 v136, s50, 8, v129
	s_ashr_i32 s13, s12, 31
	v_ashrrev_i32_e32 v137, 31, v136
	v_lshl_or_b32 v138, s49, 8, v130
	s_lshl_b64 s[12:13], s[12:13], 21
	v_lshlrev_b64 v[136:137], 12, v[136:137]
	v_ashrrev_i32_e32 v139, 31, v138
	v_lshl_add_u64 v[136:137], v[136:137], 0, s[12:13]
	v_lshl_add_u64 v[140:141], s[6:7], 0, v[136:137]
	v_lshlrev_b64 v[138:139], 2, v[138:139]
	v_lshl_add_u64 v[140:141], v[140:141], 0, v[138:139]
	global_store_dwordx4 v[140:141], v[124:127], off sc1
	global_store_dwordx4 v[140:141], v[120:123], off offset:64 sc1
	global_store_dwordx4 v[140:141], v[104:107], off offset:512 sc1
	global_store_dwordx4 v[140:141], v[96:99], off offset:576 sc1
	s_mov_b64 s[12:13], 0x80000
	s_nop 0
	v_or_b32_e32 v96, 0x10000, v136
	v_mov_b32_e32 v97, v137
	v_lshl_add_u64 v[96:97], s[6:7], 0, v[96:97]
	v_lshl_add_u64 v[96:97], v[96:97], 0, v[138:139]
	global_store_dwordx4 v[96:97], v[116:119], off sc1
	global_store_dwordx4 v[96:97], v[112:115], off offset:64 sc1
	global_store_dwordx4 v[96:97], v[88:91], off offset:512 sc1
	global_store_dwordx4 v[96:97], v[80:83], off offset:576 sc1
	s_nop 1
	v_or_b32_e32 v80, 0x20000, v136
	v_mov_b32_e32 v81, v137
	v_lshl_add_u64 v[80:81], s[6:7], 0, v[80:81]
	v_lshl_add_u64 v[80:81], v[80:81], 0, v[138:139]
	v_or_b32_e32 v136, 0x30000, v136
	global_store_dwordx4 v[80:81], v[108:111], off sc1
	global_store_dwordx4 v[80:81], v[100:103], off offset:64 sc1
	global_store_dwordx4 v[80:81], v[76:79], off offset:512 sc1
	global_store_dwordx4 v[80:81], v[72:75], off offset:576 sc1
	s_nop 1
	v_lshl_add_u64 v[72:73], s[6:7], 0, v[136:137]
	v_lshl_add_u64 v[72:73], v[72:73], 0, v[138:139]
	global_store_dwordx4 v[72:73], v[92:95], off sc1
	global_store_dwordx4 v[72:73], v[84:87], off offset:64 sc1
	global_store_dwordx4 v[72:73], v[68:71], off offset:512 sc1
	global_store_dwordx4 v[72:73], v[64:67], off offset:576 sc1
	s_nop 1
	v_lshl_add_u64 v[64:65], v[140:141], 0, s[12:13]
	s_mov_b32 s12, 0x80000
	v_add_co_u32_e32 v66, vcc, s12, v140
	s_mov_b64 s[12:13], 0x90000
	s_nop 0
	v_addc_co_u32_e32 v67, vcc, 0, v141, vcc
	global_store_dwordx4 v[66:67], v[60:63], off sc1
	global_store_dwordx4 v[64:65], v[56:59], off offset:64 sc1
	global_store_dwordx4 v[64:65], v[44:47], off offset:512 sc1
	global_store_dwordx4 v[64:65], v[36:39], off offset:576 sc1
	s_nop 1
	v_lshl_add_u64 v[36:37], v[140:141], 0, s[12:13]
	s_mov_b32 s12, 0x90000
	v_add_co_u32_e32 v38, vcc, s12, v140
	s_mov_b64 s[12:13], 0xa0000
	s_nop 0
	v_addc_co_u32_e32 v39, vcc, 0, v141, vcc
	global_store_dwordx4 v[38:39], v[52:55], off sc1
	global_store_dwordx4 v[36:37], v[48:51], off offset:64 sc1
	global_store_dwordx4 v[36:37], v[28:31], off offset:512 sc1
	global_store_dwordx4 v[36:37], v[20:23], off offset:576 sc1
	s_nop 1
	v_lshl_add_u64 v[20:21], v[140:141], 0, s[12:13]
	s_mov_b32 s12, 0xa0000
	v_add_co_u32_e32 v22, vcc, s12, v140
	s_mov_b64 s[12:13], 0xb0000
	s_nop 0
	v_addc_co_u32_e32 v23, vcc, 0, v141, vcc
	global_store_dwordx4 v[22:23], v[40:43], off sc1
	global_store_dwordx4 v[20:21], v[32:35], off offset:64 sc1
	global_store_dwordx4 v[20:21], v[12:15], off offset:512 sc1
	global_store_dwordx4 v[20:21], v[8:11], off offset:576 sc1
	s_nop 1
	v_add_co_u32_e32 v10, vcc, 0xb0000, v140
	v_lshl_add_u64 v[8:9], v[140:141], 0, s[12:13]
	s_nop 0
	v_addc_co_u32_e32 v11, vcc, 0, v141, vcc
	s_and_b64 vcc, exec, s[2:3]
	s_mov_b64 s[2:3], -1
	global_store_dwordx4 v[10:11], v[24:27], off sc1
	global_store_dwordx4 v[8:9], v[16:19], off offset:64 sc1
	global_store_dwordx4 v[8:9], v[4:7], off offset:512 sc1
	global_store_dwordx4 v[8:9], v[0:3], off offset:576 sc1
	s_cbranch_vccnz .LBB0_1344
	s_andn2_b64 vcc, exec, s[4:5]
	s_cbranch_vccnz .LBB0_1343
	v_writelane_b32 v255, 1, 53
	s_branch .LBB0_1343

.LBB0_2243:
	v_lshl_add_u32 v192, s20, 8, v209
	v_add_u32_e32 v130, 0xffffc000, v192
	v_ashrrev_i32_e32 v193, 31, v192
	v_cmp_gt_i32_e32 vcc, s41, v192
	v_lshl_or_b32 v128, s21, 8, v211
	v_mov_b32_e32 v134, s7
	v_cndmask_b32_e32 v131, 0, v193, vcc
	v_cndmask_b32_e32 v130, v130, v192, vcc
	v_mov_b32_e32 v135, s89
	v_mov_b32_e32 v136, s6
	v_mov_b32_e32 v137, s88
	v_ashrrev_i32_e32 v129, 31, v128
	v_cndmask_b32_e32 v133, v134, v135, vcc
	v_cndmask_b32_e32 v132, v136, v137, vcc
	v_lshlrev_b64 v[130:131], 12, v[130:131]
	v_lshl_add_u64 v[130:131], v[132:133], 0, v[130:131]
	v_lshlrev_b64 v[190:191], 2, v[128:129]
	v_lshl_add_u64 v[128:129], v[130:131], 0, v[190:191]
	v_or_b32_e32 v198, 16, v192
	global_load_dwordx4 v[172:175], v[128:129], off
	global_load_dwordx4 v[168:171], v[128:129], off offset:64
	global_load_dwordx4 v[164:167], v[128:129], off offset:512
	global_load_dwordx4 v[156:159], v[128:129], off offset:576
	v_ashrrev_i32_e32 v199, 31, v198
	v_add_u32_e32 v128, 0xffffc010, v192
	v_cmp_gt_i32_e32 vcc, s41, v198
	v_or_b32_e32 v196, 32, v192
	v_ashrrev_i32_e32 v197, 31, v196
	v_cndmask_b32_e32 v129, 0, v199, vcc
	v_cndmask_b32_e32 v128, v128, v198, vcc
	v_cndmask_b32_e32 v131, v134, v135, vcc
	v_cndmask_b32_e32 v130, v136, v137, vcc
	v_lshlrev_b64 v[128:129], 12, v[128:129]
	v_lshl_add_u64 v[128:129], v[130:131], 0, v[128:129]
	v_lshl_add_u64 v[128:129], v[128:129], 0, v[190:191]
	global_load_dwordx4 v[160:163], v[128:129], off
	global_load_dwordx4 v[152:155], v[128:129], off offset:64
	global_load_dwordx4 v[148:151], v[128:129], off offset:512
	global_load_dwordx4 v[140:143], v[128:129], off offset:576
	v_add_u32_e32 v128, 0xffffc020, v192
	v_cmp_gt_i32_e32 vcc, s41, v196
	v_or_b32_e32 v200, 48, v192
	s_nop 0
	v_cndmask_b32_e32 v129, 0, v197, vcc
	v_cndmask_b32_e32 v128, v128, v196, vcc
	v_cndmask_b32_e32 v131, v134, v135, vcc
	v_cndmask_b32_e32 v130, v136, v137, vcc
	v_lshlrev_b64 v[128:129], 12, v[128:129]
	v_lshl_add_u64 v[128:129], v[130:131], 0, v[128:129]
	v_lshl_add_u64 v[128:129], v[128:129], 0, v[190:191]
	global_load_dwordx4 v[144:147], v[128:129], off
	global_load_dwordx4 v[136:139], v[128:129], off offset:64
	global_load_dwordx4 v[132:135], v[128:129], off offset:512
	s_nop 0
	global_load_dwordx4 v[128:131], v[128:129], off offset:576
	v_cmp_lt_i32_e32 vcc, s47, v200
	s_and_saveexec_b64 s[20:21], vcc
	s_xor_b64 s[20:21], exec, s[20:21]
	v_add_u32_e32 v180, 0xffffc030, v192
	v_lshlrev_b64 v[194:195], 12, v[180:181]
	v_mov_b32_e32 v201, v181
	v_lshl_add_u64 v[202:203], s[6:7], 0, v[194:195]
	v_lshlrev_b64 v[194:195], 12, v[200:201]
	s_andn2_saveexec_b64 s[20:21], s[20:21]
	v_ashrrev_i32_e32 v201, 31, v200
	v_lshlrev_b64 v[194:195], 12, v[200:201]
	v_lshl_add_u64 v[202:203], s[88:89], 0, v[194:195]
	s_or_b64 exec, exec, s[20:21]
	v_lshl_add_u64 v[224:225], v[202:203], 0, v[190:191]
	global_load_dwordx4 v[200:203], v[224:225], off
	global_load_dwordx4 v[216:219], v[224:225], off offset:64
	global_load_dwordx4 v[220:223], v[224:225], off offset:512
	s_nop 0
	global_load_dwordx4 v[224:227], v[224:225], off offset:576
	v_lshlrev_b64 v[228:229], 12, v[192:193]
	v_lshl_add_u64 v[228:229], s[88:89], 0, v[228:229]
	v_lshl_add_u64 v[228:229], v[228:229], 0, v[190:191]
	s_waitcnt vmcnt(0)
	v_pk_add_f32 v[110:111], v[110:111], v[158:159]
	v_pk_add_f32 v[108:109], v[108:109], v[156:157]
	global_store_dwordx4 v[228:229], v[108:111], off offset:576 sc1
	v_pk_add_f32 v[118:119], v[118:119], v[166:167]
	v_pk_add_f32 v[116:117], v[116:117], v[164:165]
	v_lshlrev_b64 v[108:109], 12, v[198:199]
	v_lshl_add_u64 v[108:109], s[88:89], 0, v[108:109]
	global_store_dwordx4 v[228:229], v[116:119], off offset:512 sc1
	v_pk_add_f32 v[94:95], v[94:95], v[142:143]
	v_pk_add_f32 v[92:93], v[92:93], v[140:141]
	v_lshl_add_u64 v[116:117], v[108:109], 0, v[190:191]
	global_store_dwordx4 v[116:117], v[92:95], off offset:576 sc1
	v_pk_add_f32 v[102:103], v[102:103], v[150:151]
	v_pk_add_f32 v[100:101], v[100:101], v[148:149]
	v_lshlrev_b64 v[92:93], 12, v[196:197]
	v_lshl_add_u64 v[92:93], s[88:89], 0, v[92:93]
	global_store_dwordx4 v[116:117], v[100:103], off offset:512 sc1
	v_pk_add_f32 v[74:75], v[74:75], v[130:131]
	v_pk_add_f32 v[72:73], v[72:73], v[128:129]
	v_lshl_add_u64 v[100:101], v[92:93], 0, v[190:191]
	v_pk_add_f32 v[82:83], v[82:83], v[134:135]
	v_pk_add_f32 v[80:81], v[80:81], v[132:133]
	global_store_dwordx4 v[100:101], v[72:75], off offset:576 sc1
	v_pk_add_f32 v[126:127], v[126:127], v[174:175]
	v_pk_add_f32 v[124:125], v[124:125], v[172:173]
	v_lshl_add_u64 v[72:73], s[88:89], 0, v[194:195]
	v_pk_add_f32 v[122:123], v[122:123], v[170:171]
	v_pk_add_f32 v[120:121], v[120:121], v[168:169]
	v_pk_add_f32 v[110:111], v[114:115], v[162:163]
	v_pk_add_f32 v[108:109], v[112:113], v[160:161]
	v_pk_add_f32 v[106:107], v[106:107], v[154:155]
	v_pk_add_f32 v[104:105], v[104:105], v[152:153]
	v_pk_add_f32 v[94:95], v[98:99], v[146:147]
	v_pk_add_f32 v[92:93], v[96:97], v[144:145]
	v_pk_add_f32 v[90:91], v[90:91], v[138:139]
	v_pk_add_f32 v[88:89], v[88:89], v[136:137]
	global_store_dwordx4 v[100:101], v[80:83], off offset:512 sc1
	v_pk_add_f32 v[74:75], v[86:87], v[202:203]
	global_store_dwordx4 v[228:229], v[124:127], off sc1
	v_lshl_add_u64 v[80:81], v[72:73], 0, v[190:191]
	v_pk_add_f32 v[72:73], v[84:85], v[200:201]
	global_store_dwordx4 v[228:229], v[120:123], off offset:64 sc1
	global_store_dwordx4 v[116:117], v[108:111], off sc1
	global_store_dwordx4 v[116:117], v[104:107], off offset:64 sc1
	global_store_dwordx4 v[100:101], v[92:95], off sc1
	global_store_dwordx4 v[100:101], v[88:91], off offset:64 sc1
	global_store_dwordx4 v[80:81], v[72:75], off sc1
	v_pk_add_f32 v[70:71], v[70:71], v[222:223]
	v_pk_add_f32 v[68:69], v[68:69], v[220:221]
	v_pk_add_f32 v[74:75], v[78:79], v[218:219]
	v_pk_add_f32 v[72:73], v[76:77], v[216:217]
	v_pk_add_f32 v[66:67], v[66:67], v[226:227]
	v_pk_add_f32 v[64:65], v[64:65], v[224:225]
	global_store_dwordx4 v[80:81], v[72:75], off offset:64 sc1
	global_store_dwordx4 v[80:81], v[68:71], off offset:512 sc1
	global_store_dwordx4 v[80:81], v[64:67], off offset:576 sc1
	v_add_u32_e32 v118, 0x80, v192
	v_ashrrev_i32_e32 v119, 31, v118
	v_add_u32_e32 v64, 0xffffc080, v192
	v_cmp_gt_i32_e32 vcc, s48, v192
	v_mov_b32_e32 v68, s7
	v_mov_b32_e32 v69, s89
	v_cndmask_b32_e32 v65, 0, v119, vcc
	v_cndmask_b32_e32 v64, v64, v118, vcc
	v_mov_b32_e32 v70, s6
	v_mov_b32_e32 v71, s88
	v_cndmask_b32_e32 v67, v68, v69, vcc
	v_cndmask_b32_e32 v66, v70, v71, vcc
	v_lshlrev_b64 v[64:65], 12, v[64:65]
	v_lshl_add_u64 v[64:65], v[66:67], 0, v[64:65]
	v_lshl_add_u64 v[64:65], v[64:65], 0, v[190:191]
	v_add_u32_e32 v116, 0x90, v192
	global_load_dwordx4 v[108:111], v[64:65], off
	global_load_dwordx4 v[104:107], v[64:65], off offset:64
	global_load_dwordx4 v[100:103], v[64:65], off offset:512
	global_load_dwordx4 v[92:95], v[64:65], off offset:576
	v_ashrrev_i32_e32 v117, 31, v116
	v_add_u32_e32 v64, 0xffffc090, v192
	v_cmp_gt_i32_e32 vcc, s49, v192
	v_add_u32_e32 v114, 0xa0, v192
	v_ashrrev_i32_e32 v115, 31, v114
	v_cndmask_b32_e32 v65, 0, v117, vcc
	v_cndmask_b32_e32 v64, v64, v116, vcc
	v_cndmask_b32_e32 v67, v68, v69, vcc
	v_cndmask_b32_e32 v66, v70, v71, vcc
	v_lshlrev_b64 v[64:65], 12, v[64:65]
	v_lshl_add_u64 v[64:65], v[66:67], 0, v[64:65]
	v_lshl_add_u64 v[64:65], v[64:65], 0, v[190:191]
	global_load_dwordx4 v[96:99], v[64:65], off
	global_load_dwordx4 v[88:91], v[64:65], off offset:64
	global_load_dwordx4 v[84:87], v[64:65], off offset:512
	global_load_dwordx4 v[76:79], v[64:65], off offset:576
	v_add_u32_e32 v64, 0xffffc0a0, v192
	v_cmp_gt_i32_e32 vcc, s50, v192
	v_add_u32_e32 v120, 0xb0, v192
	s_nop 0
	v_cndmask_b32_e32 v65, 0, v115, vcc
	v_cndmask_b32_e32 v64, v64, v114, vcc
	v_cndmask_b32_e32 v67, v68, v69, vcc
	v_cndmask_b32_e32 v66, v70, v71, vcc
	v_lshlrev_b64 v[64:65], 12, v[64:65]
	v_lshl_add_u64 v[64:65], v[66:67], 0, v[64:65]
	v_lshl_add_u64 v[64:65], v[64:65], 0, v[190:191]
	global_load_dwordx4 v[80:83], v[64:65], off
	global_load_dwordx4 v[72:75], v[64:65], off offset:64
	global_load_dwordx4 v[68:71], v[64:65], off offset:512
	s_nop 0
	global_load_dwordx4 v[64:67], v[64:65], off offset:576
	v_cmp_lt_i32_e32 vcc, s51, v192
	s_and_saveexec_b64 s[20:21], vcc
	s_xor_b64 s[20:21], exec, s[20:21]
	v_add_u32_e32 v180, 0xffffc0b0, v192
	v_lshlrev_b64 v[112:113], 12, v[180:181]
	v_mov_b32_e32 v121, v181
	v_lshl_add_u64 v[122:123], s[6:7], 0, v[112:113]
	v_lshlrev_b64 v[112:113], 12, v[120:121]
	s_andn2_saveexec_b64 s[20:21], s[20:21]
	v_ashrrev_i32_e32 v121, 31, v120
	v_lshlrev_b64 v[112:113], 12, v[120:121]
	v_lshl_add_u64 v[122:123], s[88:89], 0, v[112:113]
	s_or_b64 exec, exec, s[20:21]
	v_lshl_add_u64 v[132:133], v[122:123], 0, v[190:191]
	global_load_dwordx4 v[120:123], v[132:133], off
	global_load_dwordx4 v[124:127], v[132:133], off offset:64
	global_load_dwordx4 v[128:131], v[132:133], off offset:512
	s_nop 0
	global_load_dwordx4 v[132:135], v[132:133], off offset:576
	v_lshlrev_b64 v[118:119], 12, v[118:119]
	v_lshl_add_u64 v[118:119], s[88:89], 0, v[118:119]
	v_lshl_add_u64 v[118:119], v[118:119], 0, v[190:191]
	s_waitcnt vmcnt(12)
	v_pk_add_f32 v[46:47], v[46:47], v[94:95]
	v_pk_add_f32 v[44:45], v[44:45], v[92:93]
	global_store_dwordx4 v[118:119], v[44:47], off offset:576 sc1
	v_pk_add_f32 v[54:55], v[54:55], v[102:103]
	v_pk_add_f32 v[52:53], v[52:53], v[100:101]
	v_lshlrev_b64 v[44:45], 12, v[116:117]
	v_lshl_add_u64 v[44:45], s[88:89], 0, v[44:45]
	global_store_dwordx4 v[118:119], v[52:55], off offset:512 sc1
	s_waitcnt vmcnt(10)
	v_pk_add_f32 v[30:31], v[30:31], v[78:79]
	v_pk_add_f32 v[28:29], v[28:29], v[76:77]
	v_lshl_add_u64 v[52:53], v[44:45], 0, v[190:191]
	global_store_dwordx4 v[52:53], v[28:31], off offset:576 sc1
	v_pk_add_f32 v[38:39], v[38:39], v[86:87]
	v_pk_add_f32 v[36:37], v[36:37], v[84:85]
	v_lshlrev_b64 v[28:29], 12, v[114:115]
	v_lshl_add_u64 v[28:29], s[88:89], 0, v[28:29]
	global_store_dwordx4 v[52:53], v[36:39], off offset:512 sc1
	s_waitcnt vmcnt(8)
	v_pk_add_f32 v[10:11], v[10:11], v[66:67]
	v_pk_add_f32 v[8:9], v[8:9], v[64:65]
	v_lshl_add_u64 v[36:37], v[28:29], 0, v[190:191]
	v_pk_add_f32 v[18:19], v[18:19], v[70:71]
	v_pk_add_f32 v[16:17], v[16:17], v[68:69]
	global_store_dwordx4 v[36:37], v[8:11], off offset:576 sc1
	v_pk_add_f32 v[62:63], v[62:63], v[110:111]
	v_pk_add_f32 v[60:61], v[60:61], v[108:109]
	v_lshl_add_u64 v[8:9], s[88:89], 0, v[112:113]
	v_pk_add_f32 v[58:59], v[58:59], v[106:107]
	v_pk_add_f32 v[56:57], v[56:57], v[104:105]
	v_pk_add_f32 v[46:47], v[50:51], v[98:99]
	v_pk_add_f32 v[44:45], v[48:49], v[96:97]
	v_pk_add_f32 v[42:43], v[42:43], v[90:91]
	v_pk_add_f32 v[40:41], v[40:41], v[88:89]
	v_pk_add_f32 v[30:31], v[34:35], v[82:83]
	v_pk_add_f32 v[28:29], v[32:33], v[80:81]
	v_pk_add_f32 v[26:27], v[26:27], v[74:75]
	v_pk_add_f32 v[24:25], v[24:25], v[72:73]
	global_store_dwordx4 v[36:37], v[16:19], off offset:512 sc1
	s_waitcnt vmcnt(9)
	v_pk_add_f32 v[10:11], v[22:23], v[122:123]
	global_store_dwordx4 v[118:119], v[60:63], off sc1
	v_lshl_add_u64 v[16:17], v[8:9], 0, v[190:191]
	v_pk_add_f32 v[8:9], v[20:21], v[120:121]
	global_store_dwordx4 v[118:119], v[56:59], off offset:64 sc1
	global_store_dwordx4 v[52:53], v[44:47], off sc1
	global_store_dwordx4 v[52:53], v[40:43], off offset:64 sc1
	global_store_dwordx4 v[36:37], v[28:31], off sc1
	global_store_dwordx4 v[36:37], v[24:27], off offset:64 sc1
	global_store_dwordx4 v[16:17], v[8:11], off sc1
	s_waitcnt vmcnt(14)
	v_pk_add_f32 v[6:7], v[6:7], v[130:131]
	v_pk_add_f32 v[4:5], v[4:5], v[128:129]
	v_pk_add_f32 v[10:11], v[14:15], v[126:127]
	v_pk_add_f32 v[8:9], v[12:13], v[124:125]
	s_waitcnt vmcnt(13)
	v_pk_add_f32 v[2:3], v[2:3], v[134:135]
	v_pk_add_f32 v[0:1], v[0:1], v[132:133]
	global_store_dwordx4 v[16:17], v[8:11], off offset:64 sc1
	global_store_dwordx4 v[16:17], v[4:7], off offset:512 sc1
	global_store_dwordx4 v[16:17], v[0:3], off offset:576 sc1
	s_andn2_b64 vcc, exec, s[2:3]
	s_mov_b64 s[2:3], -1
	s_cbranch_vccnz .LBB0_2232
	s_andn2_b64 vcc, exec, s[0:1]
	s_cbranch_vccnz .LBB0_2231
	v_writelane_b32 v255, 1, 53
	s_branch .LBB0_2231

.LBB0_2265:
	s_ashr_i32 s19, s48, 31
	s_lshr_b32 s19, s19, 24
	s_add_i32 s19, s48, s19
	s_ashr_i32 s28, s19, 8
	v_lshl_add_u32 v136, s47, 8, v128
	s_ashr_i32 s29, s28, 31
	v_ashrrev_i32_e32 v137, 31, v136
	v_lshl_or_b32 v138, s46, 8, v129
	s_lshl_b64 s[28:29], s[28:29], 21
	v_lshlrev_b64 v[136:137], 12, v[136:137]
	v_ashrrev_i32_e32 v139, 31, v138
	v_lshl_add_u64 v[136:137], v[136:137], 0, s[28:29]
	v_lshl_add_u64 v[140:141], s[6:7], 0, v[136:137]
	v_lshlrev_b64 v[138:139], 2, v[138:139]
	v_lshl_add_u64 v[140:141], v[140:141], 0, v[138:139]
	global_store_dwordx4 v[140:141], v[24:27], off sc1
	global_store_dwordx4 v[140:141], v[28:31], off offset:64 sc1
	global_store_dwordx4 v[140:141], v[56:59], off offset:512 sc1
	global_store_dwordx4 v[140:141], v[60:63], off offset:576 sc1
	v_or_b32_e32 v24, 0x10000, v136
	v_mov_b32_e32 v25, v137
	v_lshl_add_u64 v[24:25], s[6:7], 0, v[24:25]
	v_lshl_add_u64 v[24:25], v[24:25], 0, v[138:139]
	global_store_dwordx4 v[24:25], v[16:19], off sc1
	global_store_dwordx4 v[24:25], v[20:23], off offset:64 sc1
	global_store_dwordx4 v[24:25], v[48:51], off offset:512 sc1
	global_store_dwordx4 v[24:25], v[52:55], off offset:576 sc1
	v_or_b32_e32 v16, 0x20000, v136
	v_mov_b32_e32 v17, v137
	v_lshl_add_u64 v[16:17], s[6:7], 0, v[16:17]
	v_lshl_add_u64 v[16:17], v[16:17], 0, v[138:139]
	v_or_b32_e32 v136, 0x30000, v136
	global_store_dwordx4 v[16:17], v[8:11], off sc1
	global_store_dwordx4 v[16:17], v[12:15], off offset:64 sc1
	global_store_dwordx4 v[16:17], v[40:43], off offset:512 sc1
	global_store_dwordx4 v[16:17], v[44:47], off offset:576 sc1
	v_lshl_add_u64 v[8:9], s[6:7], 0, v[136:137]
	v_lshl_add_u64 v[8:9], v[8:9], 0, v[138:139]
	global_store_dwordx4 v[8:9], v[0:3], off sc1
	global_store_dwordx4 v[8:9], v[4:7], off offset:64 sc1
	global_store_dwordx4 v[8:9], v[32:35], off offset:512 sc1
	global_store_dwordx4 v[8:9], v[36:39], off offset:576 sc1
	v_add_co_u32_e32 v2, vcc, s58, v140
	v_lshl_add_u64 v[0:1], v[140:141], 0, s[10:11]
	s_nop 0
	v_addc_co_u32_e32 v3, vcc, 0, v141, vcc
	global_store_dwordx4 v[2:3], v[92:95], off sc1
	global_store_dwordx4 v[0:1], v[100:103], off offset:64 sc1
	global_store_dwordx4 v[0:1], v[120:123], off offset:512 sc1
	global_store_dwordx4 v[0:1], v[124:127], off offset:576 sc1
	v_add_co_u32_e32 v2, vcc, s59, v140
	v_lshl_add_u64 v[0:1], v[140:141], 0, s[12:13]
	s_nop 0
	v_addc_co_u32_e32 v3, vcc, 0, v141, vcc
	global_store_dwordx4 v[2:3], v[80:83], off sc1
	global_store_dwordx4 v[0:1], v[84:87], off offset:64 sc1
	global_store_dwordx4 v[0:1], v[112:115], off offset:512 sc1
	global_store_dwordx4 v[0:1], v[116:119], off offset:576 sc1
	v_add_co_u32_e32 v2, vcc, s60, v140
	v_lshl_add_u64 v[0:1], v[140:141], 0, s[14:15]
	s_nop 0
	v_addc_co_u32_e32 v3, vcc, 0, v141, vcc
	global_store_dwordx4 v[2:3], v[72:75], off sc1
	global_store_dwordx4 v[0:1], v[76:79], off offset:64 sc1
	global_store_dwordx4 v[0:1], v[104:107], off offset:512 sc1
	global_store_dwordx4 v[0:1], v[108:111], off offset:576 sc1
	v_add_co_u32_e32 v2, vcc, 0xb0000, v140
	v_lshl_add_u64 v[0:1], v[140:141], 0, s[16:17]
	s_nop 0
	v_addc_co_u32_e32 v3, vcc, 0, v141, vcc
	s_andn2_b64 vcc, exec, s[24:25]
	s_mov_b64 s[24:25], -1
	global_store_dwordx4 v[2:3], v[64:67], off sc1
	global_store_dwordx4 v[0:1], v[68:71], off offset:64 sc1
	global_store_dwordx4 v[0:1], v[88:91], off offset:512 sc1
	global_store_dwordx4 v[0:1], v[96:99], off offset:576 sc1
	s_cbranch_vccnz .LBB0_2260
	s_andn2_b64 vcc, exec, s[0:1]
	s_cbranch_vccnz .LBB0_2259
	s_barrier
	s_branch .LBB0_2259

.LBB0_2479:
	v_lshl_add_u32 v192, s48, 8, v209
	v_add_u32_e32 v130, 0xffffc000, v192
	v_ashrrev_i32_e32 v193, 31, v192
	v_cmp_gt_i32_e32 vcc, s28, v192
	v_lshl_or_b32 v128, s49, 8, v211
	v_mov_b32_e32 v134, s9
	v_cndmask_b32_e32 v131, 0, v193, vcc
	v_cndmask_b32_e32 v130, v130, v192, vcc
	v_mov_b32_e32 v135, s89
	v_mov_b32_e32 v136, s8
	v_mov_b32_e32 v137, s88
	v_ashrrev_i32_e32 v129, 31, v128
	v_cndmask_b32_e32 v133, v134, v135, vcc
	v_cndmask_b32_e32 v132, v136, v137, vcc
	v_lshlrev_b64 v[130:131], 12, v[130:131]
	v_lshl_add_u64 v[130:131], v[132:133], 0, v[130:131]
	v_lshlrev_b64 v[190:191], 2, v[128:129]
	v_lshl_add_u64 v[128:129], v[130:131], 0, v[190:191]
	v_or_b32_e32 v198, 16, v192
	global_load_dwordx4 v[172:175], v[128:129], off
	global_load_dwordx4 v[168:171], v[128:129], off offset:64
	global_load_dwordx4 v[164:167], v[128:129], off offset:512
	global_load_dwordx4 v[156:159], v[128:129], off offset:576
	v_ashrrev_i32_e32 v199, 31, v198
	v_add_u32_e32 v128, 0xffffc010, v192
	v_cmp_gt_i32_e32 vcc, s28, v198
	v_or_b32_e32 v196, 32, v192
	v_ashrrev_i32_e32 v197, 31, v196
	v_cndmask_b32_e32 v129, 0, v199, vcc
	v_cndmask_b32_e32 v128, v128, v198, vcc
	v_cndmask_b32_e32 v131, v134, v135, vcc
	v_cndmask_b32_e32 v130, v136, v137, vcc
	v_lshlrev_b64 v[128:129], 12, v[128:129]
	v_lshl_add_u64 v[128:129], v[130:131], 0, v[128:129]
	v_lshl_add_u64 v[128:129], v[128:129], 0, v[190:191]
	global_load_dwordx4 v[160:163], v[128:129], off
	global_load_dwordx4 v[152:155], v[128:129], off offset:64
	global_load_dwordx4 v[148:151], v[128:129], off offset:512
	global_load_dwordx4 v[140:143], v[128:129], off offset:576
	v_add_u32_e32 v128, 0xffffc020, v192
	v_cmp_gt_i32_e32 vcc, s28, v196
	v_or_b32_e32 v200, 48, v192
	s_nop 0
	v_cndmask_b32_e32 v129, 0, v197, vcc
	v_cndmask_b32_e32 v128, v128, v196, vcc
	v_cndmask_b32_e32 v131, v134, v135, vcc
	v_cndmask_b32_e32 v130, v136, v137, vcc
	v_lshlrev_b64 v[128:129], 12, v[128:129]
	v_lshl_add_u64 v[128:129], v[130:131], 0, v[128:129]
	v_lshl_add_u64 v[128:129], v[128:129], 0, v[190:191]
	global_load_dwordx4 v[144:147], v[128:129], off
	global_load_dwordx4 v[136:139], v[128:129], off offset:64
	global_load_dwordx4 v[132:135], v[128:129], off offset:512
	s_nop 0
	global_load_dwordx4 v[128:131], v[128:129], off offset:576
	v_cmp_lt_i32_e32 vcc, s37, v200
	s_and_saveexec_b64 s[16:17], vcc
	s_xor_b64 s[16:17], exec, s[16:17]
	v_add_u32_e32 v180, 0xffffc030, v192
	v_lshlrev_b64 v[194:195], 12, v[180:181]
	v_mov_b32_e32 v201, v181
	v_lshl_add_u64 v[202:203], s[8:9], 0, v[194:195]
	v_lshlrev_b64 v[194:195], 12, v[200:201]
	s_andn2_saveexec_b64 s[16:17], s[16:17]
	v_ashrrev_i32_e32 v201, 31, v200
	v_lshlrev_b64 v[194:195], 12, v[200:201]
	v_lshl_add_u64 v[202:203], s[88:89], 0, v[194:195]
	s_or_b64 exec, exec, s[16:17]
	v_lshl_add_u64 v[224:225], v[202:203], 0, v[190:191]
	global_load_dwordx4 v[200:203], v[224:225], off
	global_load_dwordx4 v[216:219], v[224:225], off offset:64
	global_load_dwordx4 v[220:223], v[224:225], off offset:512
	s_nop 0
	global_load_dwordx4 v[224:227], v[224:225], off offset:576
	v_lshlrev_b64 v[228:229], 12, v[192:193]
	v_lshl_add_u64 v[228:229], s[88:89], 0, v[228:229]
	v_lshl_add_u64 v[228:229], v[228:229], 0, v[190:191]
	s_waitcnt vmcnt(0)
	v_pk_add_f32 v[110:111], v[110:111], v[158:159]
	v_pk_add_f32 v[108:109], v[108:109], v[156:157]
	global_store_dwordx4 v[228:229], v[108:111], off offset:576 sc1
	v_pk_add_f32 v[118:119], v[118:119], v[166:167]
	v_pk_add_f32 v[116:117], v[116:117], v[164:165]
	v_lshlrev_b64 v[108:109], 12, v[198:199]
	v_lshl_add_u64 v[108:109], s[88:89], 0, v[108:109]
	global_store_dwordx4 v[228:229], v[116:119], off offset:512 sc1
	v_pk_add_f32 v[94:95], v[94:95], v[142:143]
	v_pk_add_f32 v[92:93], v[92:93], v[140:141]
	v_lshl_add_u64 v[116:117], v[108:109], 0, v[190:191]
	global_store_dwordx4 v[116:117], v[92:95], off offset:576 sc1
	v_pk_add_f32 v[102:103], v[102:103], v[150:151]
	v_pk_add_f32 v[100:101], v[100:101], v[148:149]
	v_lshlrev_b64 v[92:93], 12, v[196:197]
	v_lshl_add_u64 v[92:93], s[88:89], 0, v[92:93]
	global_store_dwordx4 v[116:117], v[100:103], off offset:512 sc1
	v_pk_add_f32 v[74:75], v[74:75], v[130:131]
	v_pk_add_f32 v[72:73], v[72:73], v[128:129]
	v_lshl_add_u64 v[100:101], v[92:93], 0, v[190:191]
	v_pk_add_f32 v[82:83], v[82:83], v[134:135]
	v_pk_add_f32 v[80:81], v[80:81], v[132:133]
	global_store_dwordx4 v[100:101], v[72:75], off offset:576 sc1
	v_pk_add_f32 v[126:127], v[126:127], v[174:175]
	v_pk_add_f32 v[124:125], v[124:125], v[172:173]
	v_lshl_add_u64 v[72:73], s[88:89], 0, v[194:195]
	v_pk_add_f32 v[122:123], v[122:123], v[170:171]
	v_pk_add_f32 v[120:121], v[120:121], v[168:169]
	v_pk_add_f32 v[110:111], v[114:115], v[162:163]
	v_pk_add_f32 v[108:109], v[112:113], v[160:161]
	v_pk_add_f32 v[106:107], v[106:107], v[154:155]
	v_pk_add_f32 v[104:105], v[104:105], v[152:153]
	v_pk_add_f32 v[94:95], v[98:99], v[146:147]
	v_pk_add_f32 v[92:93], v[96:97], v[144:145]
	v_pk_add_f32 v[90:91], v[90:91], v[138:139]
	v_pk_add_f32 v[88:89], v[88:89], v[136:137]
	global_store_dwordx4 v[100:101], v[80:83], off offset:512 sc1
	v_pk_add_f32 v[74:75], v[86:87], v[202:203]
	global_store_dwordx4 v[228:229], v[124:127], off sc1
	v_lshl_add_u64 v[80:81], v[72:73], 0, v[190:191]
	v_pk_add_f32 v[72:73], v[84:85], v[200:201]
	global_store_dwordx4 v[228:229], v[120:123], off offset:64 sc1
	global_store_dwordx4 v[116:117], v[108:111], off sc1
	global_store_dwordx4 v[116:117], v[104:107], off offset:64 sc1
	global_store_dwordx4 v[100:101], v[92:95], off sc1
	global_store_dwordx4 v[100:101], v[88:91], off offset:64 sc1
	global_store_dwordx4 v[80:81], v[72:75], off sc1
	v_pk_add_f32 v[70:71], v[70:71], v[222:223]
	v_pk_add_f32 v[68:69], v[68:69], v[220:221]
	v_pk_add_f32 v[74:75], v[78:79], v[218:219]
	v_pk_add_f32 v[72:73], v[76:77], v[216:217]
	v_pk_add_f32 v[66:67], v[66:67], v[226:227]
	v_pk_add_f32 v[64:65], v[64:65], v[224:225]
	global_store_dwordx4 v[80:81], v[72:75], off offset:64 sc1
	global_store_dwordx4 v[80:81], v[68:71], off offset:512 sc1
	global_store_dwordx4 v[80:81], v[64:67], off offset:576 sc1
	v_add_u32_e32 v118, 0x80, v192
	v_ashrrev_i32_e32 v119, 31, v118
	v_add_u32_e32 v64, 0xffffc080, v192
	v_cmp_gt_i32_e32 vcc, s38, v192
	v_mov_b32_e32 v68, s9
	v_mov_b32_e32 v69, s89
	v_cndmask_b32_e32 v65, 0, v119, vcc
	v_cndmask_b32_e32 v64, v64, v118, vcc
	v_mov_b32_e32 v70, s8
	v_mov_b32_e32 v71, s88
	v_cndmask_b32_e32 v67, v68, v69, vcc
	v_cndmask_b32_e32 v66, v70, v71, vcc
	v_lshlrev_b64 v[64:65], 12, v[64:65]
	v_lshl_add_u64 v[64:65], v[66:67], 0, v[64:65]
	v_lshl_add_u64 v[64:65], v[64:65], 0, v[190:191]
	v_add_u32_e32 v116, 0x90, v192
	global_load_dwordx4 v[108:111], v[64:65], off
	global_load_dwordx4 v[104:107], v[64:65], off offset:64
	global_load_dwordx4 v[100:103], v[64:65], off offset:512
	global_load_dwordx4 v[92:95], v[64:65], off offset:576
	v_ashrrev_i32_e32 v117, 31, v116
	v_add_u32_e32 v64, 0xffffc090, v192
	v_cmp_gt_i32_e32 vcc, s39, v192
	v_add_u32_e32 v114, 0xa0, v192
	v_ashrrev_i32_e32 v115, 31, v114
	v_cndmask_b32_e32 v65, 0, v117, vcc
	v_cndmask_b32_e32 v64, v64, v116, vcc
	v_cndmask_b32_e32 v67, v68, v69, vcc
	v_cndmask_b32_e32 v66, v70, v71, vcc
	v_lshlrev_b64 v[64:65], 12, v[64:65]
	v_lshl_add_u64 v[64:65], v[66:67], 0, v[64:65]
	v_lshl_add_u64 v[64:65], v[64:65], 0, v[190:191]
	global_load_dwordx4 v[96:99], v[64:65], off
	global_load_dwordx4 v[88:91], v[64:65], off offset:64
	global_load_dwordx4 v[84:87], v[64:65], off offset:512
	global_load_dwordx4 v[76:79], v[64:65], off offset:576
	v_add_u32_e32 v64, 0xffffc0a0, v192
	v_cmp_gt_i32_e32 vcc, s40, v192
	v_add_u32_e32 v120, 0xb0, v192
	s_nop 0
	v_cndmask_b32_e32 v65, 0, v115, vcc
	v_cndmask_b32_e32 v64, v64, v114, vcc
	v_cndmask_b32_e32 v67, v68, v69, vcc
	v_cndmask_b32_e32 v66, v70, v71, vcc
	v_lshlrev_b64 v[64:65], 12, v[64:65]
	v_lshl_add_u64 v[64:65], v[66:67], 0, v[64:65]
	v_lshl_add_u64 v[64:65], v[64:65], 0, v[190:191]
	global_load_dwordx4 v[80:83], v[64:65], off
	global_load_dwordx4 v[72:75], v[64:65], off offset:64
	global_load_dwordx4 v[68:71], v[64:65], off offset:512
	s_nop 0
	global_load_dwordx4 v[64:67], v[64:65], off offset:576
	v_cmp_lt_i32_e32 vcc, s41, v192
	s_and_saveexec_b64 s[16:17], vcc
	s_xor_b64 s[16:17], exec, s[16:17]
	v_add_u32_e32 v180, 0xffffc0b0, v192
	v_lshlrev_b64 v[112:113], 12, v[180:181]
	v_mov_b32_e32 v121, v181
	v_lshl_add_u64 v[122:123], s[8:9], 0, v[112:113]
	v_lshlrev_b64 v[112:113], 12, v[120:121]
	s_andn2_saveexec_b64 s[16:17], s[16:17]
	v_ashrrev_i32_e32 v121, 31, v120
	v_lshlrev_b64 v[112:113], 12, v[120:121]
	v_lshl_add_u64 v[122:123], s[88:89], 0, v[112:113]
	s_or_b64 exec, exec, s[16:17]
	v_lshl_add_u64 v[132:133], v[122:123], 0, v[190:191]
	global_load_dwordx4 v[120:123], v[132:133], off
	global_load_dwordx4 v[124:127], v[132:133], off offset:64
	global_load_dwordx4 v[128:131], v[132:133], off offset:512
	s_nop 0
	global_load_dwordx4 v[132:135], v[132:133], off offset:576
	v_lshlrev_b64 v[118:119], 12, v[118:119]
	v_lshl_add_u64 v[118:119], s[88:89], 0, v[118:119]
	v_lshl_add_u64 v[118:119], v[118:119], 0, v[190:191]
	s_waitcnt vmcnt(12)
	v_pk_add_f32 v[46:47], v[46:47], v[94:95]
	v_pk_add_f32 v[44:45], v[44:45], v[92:93]
	global_store_dwordx4 v[118:119], v[44:47], off offset:576 sc1
	v_pk_add_f32 v[54:55], v[54:55], v[102:103]
	v_pk_add_f32 v[52:53], v[52:53], v[100:101]
	v_lshlrev_b64 v[44:45], 12, v[116:117]
	v_lshl_add_u64 v[44:45], s[88:89], 0, v[44:45]
	global_store_dwordx4 v[118:119], v[52:55], off offset:512 sc1
	s_waitcnt vmcnt(10)
	v_pk_add_f32 v[30:31], v[30:31], v[78:79]
	v_pk_add_f32 v[28:29], v[28:29], v[76:77]
	v_lshl_add_u64 v[52:53], v[44:45], 0, v[190:191]
	global_store_dwordx4 v[52:53], v[28:31], off offset:576 sc1
	v_pk_add_f32 v[38:39], v[38:39], v[86:87]
	v_pk_add_f32 v[36:37], v[36:37], v[84:85]
	v_lshlrev_b64 v[28:29], 12, v[114:115]
	v_lshl_add_u64 v[28:29], s[88:89], 0, v[28:29]
	global_store_dwordx4 v[52:53], v[36:39], off offset:512 sc1
	s_waitcnt vmcnt(8)
	v_pk_add_f32 v[10:11], v[10:11], v[66:67]
	v_pk_add_f32 v[8:9], v[8:9], v[64:65]
	v_lshl_add_u64 v[36:37], v[28:29], 0, v[190:191]
	v_pk_add_f32 v[18:19], v[18:19], v[70:71]
	v_pk_add_f32 v[16:17], v[16:17], v[68:69]
	global_store_dwordx4 v[36:37], v[8:11], off offset:576 sc1
	v_pk_add_f32 v[62:63], v[62:63], v[110:111]
	v_pk_add_f32 v[60:61], v[60:61], v[108:109]
	v_lshl_add_u64 v[8:9], s[88:89], 0, v[112:113]
	v_pk_add_f32 v[58:59], v[58:59], v[106:107]
	v_pk_add_f32 v[56:57], v[56:57], v[104:105]
	v_pk_add_f32 v[46:47], v[50:51], v[98:99]
	v_pk_add_f32 v[44:45], v[48:49], v[96:97]
	v_pk_add_f32 v[42:43], v[42:43], v[90:91]
	v_pk_add_f32 v[40:41], v[40:41], v[88:89]
	v_pk_add_f32 v[30:31], v[34:35], v[82:83]
	v_pk_add_f32 v[28:29], v[32:33], v[80:81]
	v_pk_add_f32 v[26:27], v[26:27], v[74:75]
	v_pk_add_f32 v[24:25], v[24:25], v[72:73]
	global_store_dwordx4 v[36:37], v[16:19], off offset:512 sc1
	s_waitcnt vmcnt(9)
	v_pk_add_f32 v[10:11], v[22:23], v[122:123]
	global_store_dwordx4 v[118:119], v[60:63], off sc1
	v_lshl_add_u64 v[16:17], v[8:9], 0, v[190:191]
	v_pk_add_f32 v[8:9], v[20:21], v[120:121]
	global_store_dwordx4 v[118:119], v[56:59], off offset:64 sc1
	global_store_dwordx4 v[52:53], v[44:47], off sc1
	global_store_dwordx4 v[52:53], v[40:43], off offset:64 sc1
	global_store_dwordx4 v[36:37], v[28:31], off sc1
	global_store_dwordx4 v[36:37], v[24:27], off offset:64 sc1
	global_store_dwordx4 v[16:17], v[8:11], off sc1
	s_waitcnt vmcnt(14)
	v_pk_add_f32 v[6:7], v[6:7], v[130:131]
	v_pk_add_f32 v[4:5], v[4:5], v[128:129]
	v_pk_add_f32 v[10:11], v[14:15], v[126:127]
	v_pk_add_f32 v[8:9], v[12:13], v[124:125]
	s_waitcnt vmcnt(13)
	v_pk_add_f32 v[2:3], v[2:3], v[134:135]
	v_pk_add_f32 v[0:1], v[0:1], v[132:133]
	global_store_dwordx4 v[16:17], v[8:11], off offset:64 sc1
	global_store_dwordx4 v[16:17], v[4:7], off offset:512 sc1
	global_store_dwordx4 v[16:17], v[0:3], off offset:576 sc1
	s_and_b64 vcc, exec, s[2:3]
	s_mov_b64 s[2:3], -1
	s_cbranch_vccnz .LBB0_2464
	s_andn2_b64 vcc, exec, s[6:7]
	s_cbranch_vccnz .LBB0_2463
	v_writelane_b32 v255, 1, 53
	s_branch .LBB0_2463

.LBB0_2507:
	s_ashr_i32 s14, s59, 31
	s_lshr_b32 s14, s14, 23
	s_add_i32 s14, s59, s14
	s_ashr_i32 s14, s14, 9
	v_lshl_add_u32 v136, s58, 8, v129
	s_ashr_i32 s15, s14, 31
	v_ashrrev_i32_e32 v137, 31, v136
	v_lshl_or_b32 v138, s57, 8, v130
	s_lshl_b64 s[14:15], s[14:15], 21
	v_lshlrev_b64 v[136:137], 12, v[136:137]
	v_ashrrev_i32_e32 v139, 31, v138
	v_lshl_add_u64 v[136:137], v[136:137], 0, s[14:15]
	v_lshl_add_u64 v[140:141], s[8:9], 0, v[136:137]
	v_lshlrev_b64 v[138:139], 2, v[138:139]
	v_lshl_add_u64 v[140:141], v[140:141], 0, v[138:139]
	global_store_dwordx4 v[140:141], v[124:127], off sc1
	global_store_dwordx4 v[140:141], v[120:123], off offset:64 sc1
	global_store_dwordx4 v[140:141], v[104:107], off offset:512 sc1
	global_store_dwordx4 v[140:141], v[96:99], off offset:576 sc1
	s_nop 1
	v_or_b32_e32 v96, 0x10000, v136
	v_mov_b32_e32 v97, v137
	v_lshl_add_u64 v[96:97], s[8:9], 0, v[96:97]
	v_lshl_add_u64 v[96:97], v[96:97], 0, v[138:139]
	global_store_dwordx4 v[96:97], v[116:119], off sc1
	global_store_dwordx4 v[96:97], v[112:115], off offset:64 sc1
	global_store_dwordx4 v[96:97], v[88:91], off offset:512 sc1
	global_store_dwordx4 v[96:97], v[80:83], off offset:576 sc1
	s_nop 1
	v_or_b32_e32 v80, 0x20000, v136
	v_mov_b32_e32 v81, v137
	v_lshl_add_u64 v[80:81], s[8:9], 0, v[80:81]
	v_lshl_add_u64 v[80:81], v[80:81], 0, v[138:139]
	v_or_b32_e32 v136, 0x30000, v136
	global_store_dwordx4 v[80:81], v[108:111], off sc1
	global_store_dwordx4 v[80:81], v[100:103], off offset:64 sc1
	global_store_dwordx4 v[80:81], v[76:79], off offset:512 sc1
	global_store_dwordx4 v[80:81], v[72:75], off offset:576 sc1
	s_nop 1
	v_lshl_add_u64 v[72:73], s[8:9], 0, v[136:137]
	v_lshl_add_u64 v[72:73], v[72:73], 0, v[138:139]
	global_store_dwordx4 v[72:73], v[92:95], off sc1
	global_store_dwordx4 v[72:73], v[84:87], off offset:64 sc1
	global_store_dwordx4 v[72:73], v[68:71], off offset:512 sc1
	global_store_dwordx4 v[72:73], v[64:67], off offset:576 sc1
	s_nop 1
	v_add_co_u32_e32 v66, vcc, s60, v140
	v_lshl_add_u64 v[64:65], v[140:141], 0, s[16:17]
	s_nop 0
	v_addc_co_u32_e32 v67, vcc, 0, v141, vcc
	global_store_dwordx4 v[66:67], v[60:63], off sc1
	global_store_dwordx4 v[64:65], v[56:59], off offset:64 sc1
	global_store_dwordx4 v[64:65], v[44:47], off offset:512 sc1
	global_store_dwordx4 v[64:65], v[36:39], off offset:576 sc1
	s_nop 1
	v_add_co_u32_e32 v38, vcc, s61, v140
	v_lshl_add_u64 v[36:37], v[140:141], 0, s[18:19]
	s_nop 0
	v_addc_co_u32_e32 v39, vcc, 0, v141, vcc
	global_store_dwordx4 v[38:39], v[52:55], off sc1
	global_store_dwordx4 v[36:37], v[48:51], off offset:64 sc1
	global_store_dwordx4 v[36:37], v[28:31], off offset:512 sc1
	global_store_dwordx4 v[36:37], v[20:23], off offset:576 sc1
	s_nop 1
	v_add_co_u32_e32 v22, vcc, s62, v140
	v_lshl_add_u64 v[20:21], v[140:141], 0, s[20:21]
	s_nop 0
	v_addc_co_u32_e32 v23, vcc, 0, v141, vcc
	global_store_dwordx4 v[22:23], v[40:43], off sc1
	global_store_dwordx4 v[20:21], v[32:35], off offset:64 sc1
	global_store_dwordx4 v[20:21], v[12:15], off offset:512 sc1
	global_store_dwordx4 v[20:21], v[8:11], off offset:576 sc1
	s_nop 1
	v_add_co_u32_e32 v10, vcc, 0xb0000, v140
	v_lshl_add_u64 v[8:9], v[140:141], 0, s[4:5]
	s_nop 0
	v_addc_co_u32_e32 v11, vcc, 0, v141, vcc
	s_and_b64 vcc, exec, s[2:3]
	s_mov_b64 s[2:3], -1
	global_store_dwordx4 v[10:11], v[24:27], off sc1
	global_store_dwordx4 v[8:9], v[16:19], off offset:64 sc1
	global_store_dwordx4 v[8:9], v[4:7], off offset:512 sc1
	global_store_dwordx4 v[8:9], v[0:3], off offset:576 sc1
	s_cbranch_vccnz .LBB0_2496
	s_andn2_b64 vcc, exec, s[6:7]
	s_cbranch_vccnz .LBB0_2495
	v_writelane_b32 v255, 1, 53
	s_branch .LBB0_2495
